# v12 with the attention LDS-DMA block moved from the head of the second MFMA segment to the tail of the second softmax segment
# speedup vs baseline: 1.0155x; 1.0155x over previous
; #define AT_BAR() do { __builtin_amdgcn_sched_barrier(0); asm volatile("s_waitcnt lgkmcnt(0)\n\ts_barrier" ::: "memory"); __builtin_amdgcn_sched_barrier(0); } while (0)
; #define AT_PIN_M() asm volatile("" : "+v"(p[0]), "+v"(p[1]), "+v"(o[0][0]), "+v"(o[0][1]), "+v"(o[1][0]), "+v"(o[1][1]))
; __device__ __forceinline__ void attn_phase(LAS unsigned char* lds, const bf16_t* Qb, const bf16_t* Kimg, const bf16_t* Vimg, bf16_t* AB, int bid, int G, int wave_k) {
;     ...
;         int b_prev = 2 * AT_BUF, b_cur = 0, b_next = AT_BUF;
;         AT_ISSUE(0, 0); AT_ISSUE(1, AT_BUF);
;         asm volatile("s_waitcnt vmcnt(0)" ::: "memory"); AT_BAR();
;         if (grpB) AT_BAR();
;         for (int t = 0; t < 256; ++t) {
;             AT_MSEG(b_cur, 0, (t > 0 ? b_prev : b_cur), 2);
;             AT_PIN_M();
;             AT_BAR();
;             AT_SM(t == 0);
;             AT_BAR();
;             const bool issued = (t + 2 < 256);
;             if (issued) AT_ISSUE(t + 2, b_prev);
;             AT_MSEG(b_cur, 1, b_cur, 0);
.Lph_cont_a:
	v_add_f32_e32 v234, v234, v210
	v_add_f32_e32 v237, v237, v211
	v_cvt_pk_bf16_f32 v151, v150, v151
	v_cvt_pk_bf16_f32 v150, v148, v149
	v_cvt_pk_bf16_f32 v149, v146, v147
	v_cvt_pk_bf16_f32 v148, v144, v145
	v_cvt_pk_bf16_f32 v144, v152, v153
	v_cvt_pk_bf16_f32 v145, v154, v155
	v_cvt_pk_bf16_f32 v146, v156, v157
	v_cvt_pk_bf16_f32 v147, v158, v159
	v_cvt_pk_bf16_f32 v135, v134, v135
	v_cvt_pk_bf16_f32 v134, v132, v133
	v_cvt_pk_bf16_f32 v133, v130, v131
	v_cvt_pk_bf16_f32 v132, v128, v129
	v_cvt_pk_bf16_f32 v128, v136, v137
	v_cvt_pk_bf16_f32 v129, v138, v139
	v_cvt_pk_bf16_f32 v130, v140, v141
	v_cvt_pk_bf16_f32 v131, v142, v143
	s_waitcnt vmcnt(0)
	s_barrier
.LBB0_969:
	ds_read_b128 v[136:139], v160 offset:512
	ds_read_b128 v[140:143], v160 offset:2560
	ds_read_b128 v[154:157], v160 offset:4608
	ds_read_b128 v[210:213], v160 offset:6656
	ds_read_b128 v[222:225], v160 offset:8704
	ds_read_b128 v[230:233], v160 offset:10752
	ds_read_b128 v[238:241], v160 offset:12288
	ds_read_b128 v[242:245], v160 offset:12800
	ds_read_b128 v[246:249], v160 offset:14336
	ds_read_b128 v[250:253], v160 offset:14848
	s_setprio 1
	s_waitcnt lgkmcnt(9)
	v_mfma_f32_32x32x16_bf16 v[112:127], v[136:139], v[162:165], v[64:79]
	v_mfma_f32_32x32x16_bf16 v[96:111], v[136:139], v[186:189], v[80:95]
	s_waitcnt lgkmcnt(7)
	v_mfma_f32_32x32x16_bf16 v[112:127], v[140:143], v[166:169], v[112:127]
	v_mfma_f32_32x32x16_bf16 v[96:111], v[140:143], v[190:193], v[96:111]
	v_mfma_f32_32x32x16_bf16 v[112:127], v[154:157], v[170:173], v[112:127]
	v_mfma_f32_32x32x16_bf16 v[96:111], v[154:157], v[194:197], v[96:111]
	s_waitcnt lgkmcnt(4)
	v_mfma_f32_32x32x16_bf16 v[112:127], v[210:213], v[174:177], v[112:127]
	v_mfma_f32_32x32x16_bf16 v[96:111], v[210:213], v[198:201], v[96:111]
	v_mfma_f32_32x32x16_bf16 v[112:127], v[222:225], v[178:181], v[112:127]
	v_mfma_f32_32x32x16_bf16 v[96:111], v[222:225], v[202:205], v[96:111]
	v_mfma_f32_32x32x16_bf16 v[112:127], v[230:233], v[182:185], v[112:127]
	v_mfma_f32_32x32x16_bf16 v[96:111], v[230:233], v[206:209], v[96:111]
	s_waitcnt lgkmcnt(0)
	v_mfma_f32_32x32x16_bf16 v[48:63], v[238:241], v[148:151], v[48:63]
	v_mfma_f32_32x32x16_bf16 v[32:47], v[242:245], v[148:151], v[32:47]
	v_mfma_f32_32x32x16_bf16 v[16:31], v[238:241], v[132:135], v[16:31]
	v_mfma_f32_32x32x16_bf16 v[0:15], v[242:245], v[132:135], v[0:15]
	v_mfma_f32_32x32x16_bf16 v[48:63], v[246:249], v[144:147], v[48:63]
	v_mfma_f32_32x32x16_bf16 v[32:47], v[250:253], v[144:147], v[32:47]
	v_mfma_f32_32x32x16_bf16 v[16:31], v[246:249], v[128:131], v[16:31]
	v_mfma_f32_32x32x16_bf16 v[0:15], v[250:253], v[128:131], v[0:15]
	s_setprio 0

; #define AT_BAR() do { __builtin_amdgcn_sched_barrier(0); asm volatile("s_waitcnt lgkmcnt(0)\n\ts_barrier" ::: "memory"); __builtin_amdgcn_sched_barrier(0); } while (0)
; #define AT_VM(N) asm volatile("s_waitcnt vmcnt(" #N ")" ::: "memory")
; #define AT_PIN_M() asm volatile("" : "+v"(p[0]), "+v"(p[1]), "+v"(o[0][0]), "+v"(o[0][1]), "+v"(o[1][0]), "+v"(o[1][1]))
; __device__ __forceinline__ void attn_phase(LAS unsigned char* lds, const bf16_t* Qb, const bf16_t* Kimg, const bf16_t* Vimg, bf16_t* AB, int bid, int G, int wave_k) {
;     ...
;             const bool issued = (t + 2 < 256);
;             if (issued) AT_ISSUE(t + 2, b_prev);
;             AT_MSEG(b_cur, 1, b_cur, 0);
;             AT_PIN_M();
;             if (grpB) { if (issued) AT_VM(2); else AT_VM(0); }
;             AT_BAR();
;             AT_SM(false);
;             if (!grpB) { if (issued) AT_VM(3); else AT_VM(0); }
;             AT_BAR();
;             const int tmp = b_prev; b_prev = b_cur; b_cur = b_next; b_next = tmp;
.Lph_cont_b:
	v_add_f32_e32 v234, v234, v210
	v_add_f32_e32 v237, v237, v211
	v_cvt_pk_bf16_f32 v119, v118, v119
	v_cvt_pk_bf16_f32 v118, v116, v117
	v_cvt_pk_bf16_f32 v117, v114, v115
	v_cvt_pk_bf16_f32 v116, v112, v113
	v_cvt_pk_bf16_f32 v112, v120, v121
	v_cvt_pk_bf16_f32 v113, v122, v123
	v_cvt_pk_bf16_f32 v114, v124, v125
	v_cvt_pk_bf16_f32 v115, v126, v127
	v_cvt_pk_bf16_f32 v103, v102, v103
	v_cvt_pk_bf16_f32 v102, v100, v101
	v_cvt_pk_bf16_f32 v101, v98, v99
	v_cvt_pk_bf16_f32 v100, v96, v97
	v_cvt_pk_bf16_f32 v96, v104, v105
	v_cvt_pk_bf16_f32 v97, v106, v107
	v_cvt_pk_bf16_f32 v98, v108, v109
	v_cvt_pk_bf16_f32 v99, v110, v111
	s_cmpk_gt_u32 s61, 0xfd
	s_cbranch_scc1 .Lat_dma_done
	s_add_i32 m0, s54, s64
	s_bitcmp1_b32 s42, 0
	global_load_lds_dwordx4 v218, s[20:21]
	s_add_i32 m0, m0, 0x2000
	s_add_u32 s20, s20, 0x3000
	s_addc_u32 s21, s21, 0
	global_load_lds_dwordx4 v218, s[18:19]
	s_add_u32 s18, s18, s55
	s_addc_u32 s19, s19, 0
	s_bitcmp1_b32 s42, 0
	s_cbranch_scc1 .Lat_dma_done
	s_add_i32 m0, m0, 0x2000
	s_nop 0
	global_load_lds_dwordx4 v218, s[0:1]
	s_add_u32 s0, s0, 0x2000
	s_addc_u32 s1, s1, 0
.Lat_dma_done:
.LBB0_981:
	s_barrier
	s_add_i32 s61, s61, 1
	s_mov_b32 s16, s62
	s_mov_b32 s62, s63
	s_mov_b32 s63, s64
	s_mov_b32 s64, s16
	s_cmpk_lg_i32 s61, 0x100
	s_cbranch_scc1 .LBB0_963
	s_branch .LBB0_983
